# v16 + XCD-local barrier at the y_b->w_o and UP->down seams (run-time placement check, cross-XCD round and L2 writeback skipped)
# speedup vs baseline: 1.0144x; 1.0144x over previous
; #define LAS __attribute__((address_space(3)))
; __device__ __forceinline__ unsigned xb_add(unsigned* p, unsigned v) { return __hip_atomic_fetch_add(p, v, __ATOMIC_RELAXED, __HIP_MEMORY_SCOPE_AGENT); }
; __device__ __forceinline__ unsigned xb_xcc_id() { return (unsigned)__builtin_amdgcn_s_getreg((3 << 11) | 20) & 0xFu; }
; __device__ __forceinline__ XcdBarrier xcd_barrier_post(unsigned* bar, volatile LAS unsigned* st) {
;     XcdBarrier b; b.bar = bar; b.x = xb_xcc_id(); b.st = st;
;     if (threadIdx.x == 0) (void)xb_add(&bar[XB_XCNT(b.x)], 1u);
;     return b;
; __global__ void __launch_bounds__(NTHR, 2) fwd_kernel(Args args) {
;     extern __shared__ __attribute__((aligned(16))) unsigned char lds_raw[];
;     cg::grid_group grid = cg::this_grid();
;     Frame F; F.lds = (LAS unsigned char*)lds_raw; F.tid = threadIdx.x; F.lane = F.tid & 63; F.wave = __builtin_amdgcn_readfirstlane(F.tid >> 6); F.G = gridDim.x;
;     Ptrs A; A.x = args.in[0]; A.mix_norm = args.in[1]; A.w_in = args.in[2]; A.w_a = args.in[3]; A.w_b = args.in[4]; A.w_o = args.in[5]; A.ffn_norm = args.in[6]; A.w_up = args.in[7]; A.w_down = args.in[8]; A.final_norm = args.in[9];
;     A.out = args.out; A.ws = args.ws;
;     unsigned char* ws = args.ws;
;     unsigned* ctl = (unsigned*)(ws + WS_CTL);
;     bf16* XN = (bf16*)(ws + WS_XN); bf16* Pb = (bf16*)(ws + WS_P); bf16* Gb = (bf16*)(ws + WS_G); bf16* COMB = (bf16*)(ws + WS_COMB); bf16* RET = (bf16*)(ws + WS_RET);
;     bf16* SCR = (bf16*)(ws + WS_SCR); bf16* MRG = (bf16*)(ws + WS_MRG); bf16* Hb = (bf16*)(ws + WS_H);
;     float* PART = (float*)(ws + WS_PART); float* LSE = (float*)(ws + WS_LSE);
;     const float* ropeA = (const float*)(ws + WS_ROPEA); const float* ropeR = (const float*)(ws + WS_ROPER);
;     if (F.tid < 8) ((LAS unsigned*)(F.lds + LDS_BYTES - 32))[F.tid] = 0u;
;     __syncthreads();
;     XcdBarrier bar = xcd_barrier_post((unsigned*)(ws + WS_BAR), (volatile LAS unsigned*)(F.lds + LDS_BYTES - 32));
_Z10fwd_kernel4Args:
	s_load_dwordx8 s[56:63], s[0:1], 0x40
	s_load_dwordx4 s[76:79], s[0:1], 0x60
	s_load_dword s36, s[0:1], 0x70
	s_add_u32 s4, s0, 0x68
	s_addc_u32 s5, s1, 0
	v_and_b32_e32 v224, 0x3ff, v0
	v_writelane_b32 v253, s4, 0
	s_mov_b32 s72, s2
	v_readfirstlane_b32 s33, v224
	v_writelane_b32 v253, s5, 1
	v_cmp_gt_u32_e32 vcc, 8, v224
	s_and_saveexec_b64 s[6:7], vcc
	v_lshl_add_u32 v1, v224, 2, 0
	v_add_u32_e32 v1, 0x23fe0, v1
	v_mov_b32_e32 v2, 0
	ds_write_b32 v1, v2
	s_or_b64 exec, exec, s[6:7]
	s_waitcnt lgkmcnt(0)
	s_barrier
	s_add_u32 s50, s62, 0x1000
	s_getreg_b32 s4, hwreg(HW_REG_XCC_ID, 0, 4)
	s_addc_u32 s51, s63, 0
	s_and_b32 s37, s4, 15
	v_cmp_eq_u32_e64 s[6:7], 0, v224
	s_mov_b64 s[4:5], exec
	s_nop 0
	v_writelane_b32 v253, s6, 2
	s_nop 1
	v_writelane_b32 v253, s7, 3
	s_and_b64 s[6:7], s[4:5], s[6:7]
	s_mov_b64 exec, s[6:7]
	s_cbranch_execz .LBB0_5
	s_mov_b64 s[6:7], exec
	v_mbcnt_lo_u32_b32 v1, s6, 0
	v_mbcnt_hi_u32_b32 v1, s7, v1
	v_cmp_eq_u32_e32 vcc, 0, v1
	s_and_b64 s[8:9], exec, vcc
	s_mov_b64 exec, s[8:9]
	s_cbranch_execz .LBB0_5
	s_lshl_b32 s8, s37, 8
	s_bcnt1_i32_b64 s6, s[6:7]
	v_mov_b32_e32 v1, s8
	v_mov_b32_e32 v2, s6
	global_atomic_add v1, v2, s[50:51] offset:1024
	s_and_b32 s8, s72, 7
	s_lshl_b32 s9, 1, s37
	s_cmp_lt_u32 s37, 8
	s_cselect_b32 s9, s9, 0xff
	s_and_b32 s6, s8, 3
	s_lshl_b32 s6, s6, 3
	s_lshl_b32 s9, s9, s6
	s_and_b32 s8, s8, 4
	s_add_i32 s8, s8, 0x7000
	v_mov_b32_e32 v1, s8
	v_mov_b32_e32 v2, s9
	global_atomic_or v1, v2, s[62:63]

; __device__ __forceinline__ unsigned xb_add(unsigned* p, unsigned v) { return __hip_atomic_fetch_add(p, v, __ATOMIC_RELAXED, __HIP_MEMORY_SCOPE_AGENT); }
; __device__ __forceinline__ void xcd_barrier(const XcdBarrier& b) {
;     asm volatile("s_waitcnt vmcnt(0)" ::: "memory");
;     __syncthreads();
;     if (threadIdx.x == 0) {
;         unsigned* bar = b.bar;
;         __builtin_amdgcn_s_waitcnt(0);
;         unsigned nloc = b.st[0], nx = b.st[1];
;         if (nloc == 0u) { xcd_barrier_complete(bar, b.x, nloc, nx); b.st[0] = nloc; b.st[1] = nx; }
;         const unsigned old = xb_add(&bar[XB_XSUB(b.x)], 1u);
.LBB0_779:
	s_mov_b64 s[20:21], exec
	v_mov_b32_e32 v20, 0x7000
	global_load_dwordx2 v[20:21], v20, s[62:63] sc1
	v_mbcnt_lo_u32_b32 v0, s20, 0
	v_mbcnt_hi_u32_b32 v0, s21, v0
	v_cmp_eq_u32_e32 vcc, 0, v0
	s_and_saveexec_b64 s[18:19], vcc
	s_cbranch_execz .LBB0_781
	s_bcnt1_i32_b64 s13, s[20:21]
	v_readlane_b32 s14, v254, 27
	v_mov_b32_e32 v4, s13
	v_readlane_b32 s15, v254, 28
	s_nop 4
	global_atomic_add v4, v1, v4, s[14:15] sc0

; __device__ __forceinline__ unsigned xb_add(unsigned* p, unsigned v) { return __hip_atomic_fetch_add(p, v, __ATOMIC_RELAXED, __HIP_MEMORY_SCOPE_AGENT); }
; __device__ __forceinline__ void xcd_barrier(const XcdBarrier& b) {
;     ...
;         const unsigned old = xb_add(&bar[XB_XSUB(b.x)], 1u);
;         const unsigned gen = old / nloc;
;         if (old + 1u == (gen + 1u) * nloc) {
;             __builtin_amdgcn_fence(__ATOMIC_RELEASE, "agent");
;             asm volatile("s_waitcnt vmcnt(0)" ::: "memory");
;             const unsigned og = xb_add(&bar[XB_TOP], 1u);
;             const unsigned tg = og / nx;
;             if (og + 1u == (tg + 1u) * nx) xb_add(&bar[XB_TOPGEN], 1u);
.LBB0_795:
	s_andn2_saveexec_b64 s[14:15], s[18:19]
	s_cbranch_execz .LBB0_815
	s_mov_b64 s[18:19], exec
	v_readfirstlane_b32 s13, v20
	v_readfirstlane_b32 s14, v21
	s_sub_u32 s15, s13, 0x1010101
	s_and_b32 s13, s13, s15
	s_sub_u32 s15, s14, 0x1010101
	s_and_b32 s14, s14, s15
	s_or_b32 s13, s13, s14
	s_cmp_eq_u32 s13, 0
	s_cbranch_scc1 .LBB0_812
	buffer_wbl2 sc1
	s_waitcnt lgkmcnt(0)
	s_waitcnt vmcnt(0)
	v_mbcnt_lo_u32_b32 v0, s18, 0
	v_mbcnt_hi_u32_b32 v0, s19, v0
	v_cmp_eq_u32_e32 vcc, 0, v0
	s_and_saveexec_b64 s[20:21], vcc
	s_cbranch_execz .LBB0_798
	s_bcnt1_i32_b64 s13, s[18:19]
	v_readlane_b32 s14, v254, 31
	v_mov_b32_e32 v3, s13
	v_readlane_b32 s15, v254, 32
	s_nop 4
	global_atomic_add v3, v1, v3, s[14:15] sc0

; __device__ __forceinline__ unsigned xb_add(unsigned* p, unsigned v) { return __hip_atomic_fetch_add(p, v, __ATOMIC_RELAXED, __HIP_MEMORY_SCOPE_AGENT); }
; __device__ __forceinline__ void xcd_barrier(const XcdBarrier& b) {
;     asm volatile("s_waitcnt vmcnt(0)" ::: "memory");
;     __syncthreads();
;     if (threadIdx.x == 0) {
;         unsigned* bar = b.bar;
;         __builtin_amdgcn_s_waitcnt(0);
;         unsigned nloc = b.st[0], nx = b.st[1];
;         if (nloc == 0u) { xcd_barrier_complete(bar, b.x, nloc, nx); b.st[0] = nloc; b.st[1] = nx; }
;         const unsigned old = xb_add(&bar[XB_XSUB(b.x)], 1u);
.LBB0_993:
	s_mov_b64 s[20:21], exec
	v_mov_b32_e32 v20, 0x7000
	global_load_dwordx2 v[20:21], v20, s[62:63] sc1
	v_mbcnt_lo_u32_b32 v0, s20, 0
	v_mbcnt_hi_u32_b32 v0, s21, v0
	v_cmp_eq_u32_e32 vcc, 0, v0
	s_and_saveexec_b64 s[16:17], vcc
	s_cbranch_execz .LBB0_995
	s_bcnt1_i32_b64 s13, s[20:21]
	v_readlane_b32 s14, v254, 27
	v_mov_b32_e32 v4, s13
	v_readlane_b32 s15, v254, 28
	s_nop 4
	global_atomic_add v4, v1, v4, s[14:15] sc0

; __device__ __forceinline__ unsigned xb_add(unsigned* p, unsigned v) { return __hip_atomic_fetch_add(p, v, __ATOMIC_RELAXED, __HIP_MEMORY_SCOPE_AGENT); }
; __device__ __forceinline__ void xcd_barrier(const XcdBarrier& b) {
;     ...
;         const unsigned old = xb_add(&bar[XB_XSUB(b.x)], 1u);
;         const unsigned gen = old / nloc;
;         if (old + 1u == (gen + 1u) * nloc) {
;             __builtin_amdgcn_fence(__ATOMIC_RELEASE, "agent");
;             asm volatile("s_waitcnt vmcnt(0)" ::: "memory");
;             const unsigned og = xb_add(&bar[XB_TOP], 1u);
;             const unsigned tg = og / nx;
;             if (og + 1u == (tg + 1u) * nx) xb_add(&bar[XB_TOPGEN], 1u);
.LBB0_1009:
	s_andn2_saveexec_b64 s[14:15], s[16:17]
	s_cbranch_execz .LBB0_1029
	s_mov_b64 s[16:17], exec
	v_readfirstlane_b32 s13, v20
	v_readfirstlane_b32 s14, v21
	s_sub_u32 s15, s13, 0x1010101
	s_and_b32 s13, s13, s15
	s_sub_u32 s15, s14, 0x1010101
	s_and_b32 s14, s14, s15
	s_or_b32 s13, s13, s14
	s_cmp_eq_u32 s13, 0
	s_cbranch_scc1 .LBB0_1026
	buffer_wbl2 sc1
	s_waitcnt lgkmcnt(0)
	s_waitcnt vmcnt(0)
	v_mbcnt_lo_u32_b32 v0, s16, 0
	v_mbcnt_hi_u32_b32 v0, s17, v0
	v_cmp_eq_u32_e32 vcc, 0, v0
	s_and_saveexec_b64 s[20:21], vcc
	s_cbranch_execz .LBB0_1012
	s_bcnt1_i32_b64 s13, s[16:17]
	v_readlane_b32 s14, v254, 31
	v_mov_b32_e32 v3, s13
	v_readlane_b32 s15, v254, 32
	s_nop 4
	global_atomic_add v3, v1, v3, s[14:15] sc0
